# P0->P1 seam as a light wait: adaLN partial sums stored write-through and counted per workgroup; P1 waits for the count only (no write-back/invalidate); first full barrier moves to P1->P2
# speedup vs baseline: 1.0152x; 1.0045x over previous
.LBB0_27:
	v_add_u32_e32 v1, s0, v11
	ds_read2st64_b32 v[2:3], v1 offset1:4
	ds_read2st64_b32 v[6:7], v1 offset0:8 offset1:12
	ds_read2st64_b32 v[14:15], v1 offset0:16 offset1:20
	ds_read2st64_b32 v[16:17], v1 offset0:24 offset1:28
	s_addk_i32 s0, 0x2000
	s_waitcnt lgkmcnt(3)
	v_add_f32_e32 v0, v0, v2
	v_add_f32_e32 v0, v0, v3
	s_waitcnt lgkmcnt(2)
	v_add_f32_e32 v0, v0, v6
	v_add_f32_e32 v0, v0, v7
	s_waitcnt lgkmcnt(1)
	v_add_f32_e32 v0, v0, v14
	v_add_f32_e32 v0, v0, v15
	s_waitcnt lgkmcnt(0)
	v_add_f32_e32 v0, v0, v16
	s_cmpk_eq_u32 s0, 0x8000
	v_add_f32_e32 v0, v0, v17
	s_cbranch_scc0 .LBB0_27
	v_lshl_add_u32 v1, s5, 2, v10
	v_mov_b64_e32 v[2:3], s[44:45]
	s_ashr_i32 s5, s4, 31
	v_mad_i64_i32 v[2:3], s[0:1], v1, s3, v[2:3]
	v_lshl_add_u64 v[2:3], s[4:5], 2, v[2:3]
	v_lshl_add_u64 v[2:3], v[2:3], 0, v[4:5]
	global_store_dword v[2:3], v0, off sc1
	s_branch .LBB0_24
.LBB0_29:
	s_waitcnt vmcnt(0)
	s_barrier
	v_readfirstlane_b32 s0, v252
	s_cmp_lg_u32 s0, 0
	s_cbranch_scc1 .Lada_sig_done
	s_mov_b64 s[0:1], exec
	s_mov_b64 exec, 1
	v_mov_b32_e32 v0, 0x8000
	v_mov_b32_e32 v1, 1
	global_atomic_add v0, v1, s[54:55]
	s_mov_b64 exec, s[0:1]

.LBB0_40:
	s_waitcnt vmcnt(0)
	s_barrier
	s_mov_b64 s[4:5], exec
	v_readlane_b32 s0, v255, 1
	v_readlane_b32 s1, v255, 2
	s_and_b64 s[0:1], s[4:5], s[0:1]
	s_mov_b64 exec, s[0:1]
	s_cbranch_execz .Lgb1_others
	v_mov_b32_e32 v0, 0x8000
	s_mov_b32 s1, 0
.Lgb1_spin:
	global_load_dword v1, v0, s[54:55] sc1
	s_waitcnt vmcnt(0)
	v_readfirstlane_b32 s0, v1
	s_cmp_ge_u32 s0, s34
	s_cbranch_scc1 .LBB0_92
	s_sleep 1
	s_add_u32 s1, s1, 1
	s_cmp_lt_u32 s1, 0x40000
	s_cbranch_scc1 .Lgb1_spin
.Lgb1_others:
.LBB0_92:
	s_or_b64 exec, exec, s[4:5]
	v_mov_b32_e32 v96, v252
	s_waitcnt lgkmcnt(0)
	s_barrier
	s_mov_b32 s0, 0xc000
	v_lshl_add_u32 v0, s2, 9, v96
	v_cmp_gt_i32_e32 vcc, s0, v0
	s_and_saveexec_b64 s[4:5], vcc
	s_cbranch_execz .LBB0_95
	s_add_u32 s6, s54, 0x200000
	s_addc_u32 s7, s55, 0
	s_lshl_b32 s0, s34, 9
	s_mov_b64 s[8:9], 0
	s_mov_b32 s1, 0x2aaaaaab
	s_mov_b32 s3, 0xbfff

.LBB0_132:
	s_add_u32 s12, s54, 0x200
	s_addc_u32 s13, s55, 0
	s_add_u32 s18, s54, 0x1000
	s_addc_u32 s19, s55, 0
	s_add_u32 s20, s54, 0x1100
	s_addc_u32 s21, s55, 0
	s_add_u32 s22, s54, 0x1200
	s_addc_u32 s23, s55, 0
	s_add_u32 s24, s54, 0x1300
	s_mul_i32 s83, s35, s34
	v_readlane_b32 s0, v255, 0
	s_addc_u32 s25, s55, 0
	s_mul_i32 s83, s83, s0
	s_add_u32 s0, s54, 0x3400
	s_addc_u32 s1, s55, 0
	v_writelane_b32 v255, s0, 6
	s_barrier
	s_nop 0
	v_writelane_b32 v255, s1, 7
	s_add_u32 s0, s54, 0x3500
	s_addc_u32 s1, s55, 0
	s_waitcnt vmcnt(0)
	v_writelane_b32 v255, s0, 8
	s_barrier
	s_nop 0
	v_writelane_b32 v255, s1, 9
	s_mov_b64 s[4:5], exec
	v_readlane_b32 s0, v255, 1
	v_readlane_b32 s1, v255, 2
	s_and_b64 s[0:1], s[4:5], s[0:1]
	s_mov_b64 exec, s[0:1]
	s_cbranch_execz .Lgb2_others
	s_getreg_b32 s0, hwreg(HW_REG_XCC_ID, 0, 4)
	s_and_b32 s0, s0, 15
	s_lshl_b32 s1, s0, 8
	s_add_u32 s6, s54, s1
	s_addc_u32 s7, s55, 0
	v_mov_b32_e32 v0, 0x1000
	v_mov_b32_e32 v1, 1
	global_atomic_add v1, v0, v1, s[6:7] offset:1024 sc0
	v_readlane_b32 s1, v255, 0
	s_mul_i32 s1, s35, s1
	s_mul_i32 s15, s1, s34
	s_mov_b32 s1, 0
	v_mov_b32_e32 v0, 0x400

.LBB0_265:
	s_waitcnt vmcnt(0)
	s_waitcnt vmcnt(0) lgkmcnt(0)
	s_barrier
	s_mov_b64 s[4:5], exec
	v_readlane_b32 s0, v255, 1
	v_readlane_b32 s1, v255, 2
	s_and_b64 s[0:1], s[4:5], s[0:1]
	s_mov_b64 exec, s[0:1]
	s_cbranch_execz .Lgb3_others
	s_getreg_b32 s0, hwreg(HW_REG_XCC_ID, 0, 4)
	v_mov_b32_e32 v0, 0x23fc0
	ds_read_b64 v[2:3], v0
	s_and_b32 s0, s0, 15
	s_lshl_b32 s1, s0, 8
	s_add_u32 s6, s54, s1
	s_addc_u32 s7, s55, 0
	v_mov_b32_e32 v0, 0x1000
	v_mov_b32_e32 v1, 1
	global_atomic_add v1, v0, v1, s[6:7] offset:1024 sc0
	s_waitcnt lgkmcnt(0)
	v_readfirstlane_b32 s8, v2
	v_readfirstlane_b32 s9, v3
	s_mul_i32 s8, s8, 2
	s_mul_i32 s9, s9, 2
	v_mov_b32_e32 v0, 0x3000
	s_waitcnt vmcnt(0)
	v_readfirstlane_b32 s0, v1
	s_add_u32 s0, s0, 1
	s_cmp_lg_u32 s0, s8
	s_cbranch_scc0 .Lgb3_lead
	s_branch .Lgb3_wait

.LBB0_618:
	s_waitcnt vmcnt(0)
	s_barrier
	s_mov_b64 s[4:5], exec
	v_readlane_b32 s0, v255, 1
	v_readlane_b32 s1, v255, 2
	s_and_b64 s[0:1], s[4:5], s[0:1]
	s_mov_b64 exec, s[0:1]
	s_cbranch_execz .Lgb4_others
	s_getreg_b32 s0, hwreg(HW_REG_XCC_ID, 0, 4)
	v_mov_b32_e32 v0, 0x23fc0
	ds_read_b64 v[2:3], v0
	s_and_b32 s0, s0, 15
	s_lshl_b32 s1, s0, 8
	s_add_u32 s6, s54, s1
	s_addc_u32 s7, s55, 0
	v_mov_b32_e32 v0, 0x1000
	v_mov_b32_e32 v1, 1
	global_atomic_add v1, v0, v1, s[6:7] offset:1024 sc0
	s_waitcnt lgkmcnt(0)
	v_readfirstlane_b32 s8, v2
	v_readfirstlane_b32 s9, v3
	s_mul_i32 s8, s8, 3
	s_mul_i32 s9, s9, 3
	v_mov_b32_e32 v0, 0x3000
	s_waitcnt vmcnt(0)
	v_readfirstlane_b32 s0, v1
	s_add_u32 s0, s0, 1
	s_cmp_lg_u32 s0, s8
	s_cbranch_scc0 .Lgb4_lead
	s_branch .Lgb4_wait

.LBB0_864:
	s_or_b64 exec, exec, s[42:43]
	s_mov_b32 s47, 0
	s_mov_b32 s48, s47
	s_or_b64 s[0:1], s[48:49], s[46:47]
	s_add_u32 s4, s54, s6
	s_addc_u32 s5, s55, s7
	v_lshl_add_u64 v[2:3], s[4:5], 0, v[196:197]
	s_mov_b32 s4, 0x208000
	v_add_co_u32_e32 v4, vcc, s4, v2
	s_waitcnt lgkmcnt(0)
	s_barrier
	v_lshl_add_u64 v[0:1], s[0:1], 0, v[196:197]
	s_mov_b64 s[0:1], 0x208000
	v_addc_co_u32_e32 v5, vcc, 0, v3, vcc
	global_load_dwordx4 v[84:87], v[4:5], off
	v_lshl_add_u64 v[4:5], v[2:3], 0, s[0:1]
	s_mov_b32 s4, 0x206000
	global_load_dwordx4 v[88:91], v[4:5], off offset:64
	global_load_dwordx4 v[92:95], v[4:5], off offset:512
	global_load_dwordx4 v[96:99], v[4:5], off offset:576
	flat_load_dwordx4 v[100:103], v[0:1]
	flat_load_dwordx4 v[104:107], v[0:1] offset:64
	flat_load_dwordx4 v[108:111], v[0:1] offset:512
	flat_load_dwordx4 v[128:131], v[0:1] offset:576
	v_add_co_u32_e32 v0, vcc, s4, v2
	s_mov_b64 s[0:1], 0x206000
	s_nop 0
	v_addc_co_u32_e32 v1, vcc, 0, v3, vcc
	global_load_dwordx4 v[12:15], v[0:1], off
	v_lshl_add_u64 v[0:1], v[2:3], 0, s[0:1]
	global_load_dwordx4 v[8:11], v[0:1], off offset:64
	global_load_dwordx4 v[4:7], v[0:1], off offset:512
	s_nop 0
	global_load_dwordx4 v[0:3], v[0:1], off offset:576
	v_lshl_add_u32 v79, v215, 2, 0
	v_add_u32_e32 v196, 0x1000, v79
	ds_read2_b32 v[134:135], v196 offset1:16
	v_add_u32_e32 v78, s16, v215
	v_ashrrev_i32_e32 v79, 31, v78
	v_lshlrev_b64 v[136:137], 12, v[78:79]
	v_lshl_add_u64 v[136:137], s[26:27], 0, v[136:137]
	s_waitcnt lgkmcnt(0)
	v_pk_mul_f32 v[124:125], v[124:125], v[134:135] op_sel_hi:[1,0]
	v_pk_mul_f32 v[126:127], v[126:127], v[134:135] op_sel_hi:[1,0]
	v_pk_mul_f32 v[140:141], v[192:193], v[134:135] op_sel_hi:[1,0]
	v_pk_mul_f32 v[120:121], v[120:121], v[134:135] op_sel_hi:[1,0]
	v_pk_mul_f32 v[122:123], v[122:123], v[134:135] op_sel_hi:[1,0]
	v_pk_mul_f32 v[116:117], v[116:117], v[134:135] op_sel_hi:[1,0]
	v_pk_mul_f32 v[118:119], v[118:119], v[134:135] op_sel_hi:[1,0]
	v_pk_mul_f32 v[138:139], v[194:195], v[134:135] op_sel_hi:[1,0]
	v_add_u32_e32 v132, 16, v78
	v_lshl_add_u64 v[136:137], v[136:137], 0, v[74:75]
	v_ashrrev_i32_e32 v133, 31, v132
	s_waitcnt vmcnt(0)
	v_pk_add_f32 v[86:87], v[86:87], 1.0 op_sel_hi:[1,0]
	v_pk_add_f32 v[84:85], v[84:85], 1.0 op_sel_hi:[1,0]
	v_pk_add_f32 v[90:91], v[90:91], 1.0 op_sel_hi:[1,0]
	v_pk_add_f32 v[88:89], v[88:89], 1.0 op_sel_hi:[1,0]
	v_pk_add_f32 v[142:143], v[94:95], 1.0 op_sel_hi:[1,0]
	v_pk_add_f32 v[186:187], v[92:93], 1.0 op_sel_hi:[1,0]
	v_pk_add_f32 v[190:191], v[98:99], 1.0 op_sel_hi:[1,0]
	v_pk_add_f32 v[192:193], v[96:97], 1.0 op_sel_hi:[1,0]
	v_pk_mul_f32 v[96:97], v[102:103], v[86:87]
	v_pk_mul_f32 v[98:99], v[100:101], v[84:85]
	v_pk_mul_f32 v[92:93], v[106:107], v[90:91]
	v_pk_mul_f32 v[94:95], v[104:105], v[88:89]
	v_pk_mul_f32 v[88:89], v[110:111], v[142:143]
	v_pk_mul_f32 v[90:91], v[108:109], v[186:187]
	v_pk_mul_f32 v[84:85], v[130:131], v[190:191]
	v_pk_mul_f32 v[86:87], v[128:129], v[192:193]
	v_pk_fma_f32 v[100:101], v[96:97], v[126:127], v[14:15]
	v_pk_fma_f32 v[102:103], v[98:99], v[124:125], v[12:13]
	v_pk_fma_f32 v[104:105], v[92:93], v[122:123], v[10:11]
	v_pk_fma_f32 v[106:107], v[94:95], v[120:121], v[8:9]
	v_pk_fma_f32 v[108:109], v[88:89], v[118:119], v[6:7]
	v_pk_fma_f32 v[110:111], v[90:91], v[116:117], v[4:5]
	v_pk_fma_f32 v[116:117], v[84:85], v[140:141], v[2:3]
	v_pk_fma_f32 v[118:119], v[86:87], v[138:139], v[0:1]
	v_cvt_pk_bf16_f32 v102, v102, v103
	v_cvt_pk_bf16_f32 v103, v100, v101
	v_cvt_pk_bf16_f32 v100, v106, v107
	v_cvt_pk_bf16_f32 v101, v104, v105
	v_cvt_pk_bf16_f32 v104, v110, v111
	v_cvt_pk_bf16_f32 v105, v108, v109
	v_cvt_pk_bf16_f32 v106, v118, v119
	v_cvt_pk_bf16_f32 v107, v116, v117
	global_store_dwordx2 v[136:137], v[102:103], off
	global_store_dwordx2 v[136:137], v[100:101], off offset:32
	global_store_dwordx2 v[136:137], v[104:105], off offset:256
	global_store_dwordx2 v[136:137], v[106:107], off offset:288
	v_mov_b32_e32 v102, v135
	v_lshlrev_b64 v[100:101], 12, v[132:133]
	v_pk_mul_f32 v[104:105], v[188:189], v[102:103] op_sel_hi:[1,0]
	v_pk_mul_f32 v[106:107], v[114:115], v[102:103] op_sel_hi:[1,0]
	v_lshl_add_u64 v[100:101], s[26:27], 0, v[100:101]
	v_pk_fma_f32 v[106:107], v[96:97], v[106:107], v[14:15]
	v_pk_fma_f32 v[104:105], v[98:99], v[104:105], v[12:13]
	v_lshl_add_u64 v[100:101], v[100:101], 0, v[74:75]
	v_cvt_pk_bf16_f32 v104, v104, v105
	v_cvt_pk_bf16_f32 v105, v106, v107
	global_store_dwordx2 v[100:101], v[104:105], off
	v_pk_mul_f32 v[104:105], v[184:185], v[102:103] op_sel_hi:[1,0]
	v_pk_mul_f32 v[106:107], v[112:113], v[102:103] op_sel_hi:[1,0]
	v_pk_fma_f32 v[104:105], v[94:95], v[104:105], v[8:9]
	v_pk_fma_f32 v[106:107], v[92:93], v[106:107], v[10:11]
	v_cvt_pk_bf16_f32 v104, v104, v105
	v_cvt_pk_bf16_f32 v105, v106, v107
	global_store_dwordx2 v[100:101], v[104:105], off offset:32
	v_pk_mul_f32 v[104:105], v[180:181], v[102:103] op_sel_hi:[1,0]
	v_pk_mul_f32 v[106:107], v[182:183], v[102:103] op_sel_hi:[1,0]
	v_pk_fma_f32 v[104:105], v[90:91], v[104:105], v[4:5]
	v_pk_fma_f32 v[106:107], v[88:89], v[106:107], v[6:7]
	v_cvt_pk_bf16_f32 v104, v104, v105
	v_cvt_pk_bf16_f32 v105, v106, v107
	global_store_dwordx2 v[100:101], v[104:105], off offset:256
	v_pk_mul_f32 v[104:105], v[176:177], v[102:103] op_sel_hi:[1,0]
	v_pk_mul_f32 v[102:103], v[178:179], v[102:103] op_sel_hi:[1,0]
	v_pk_fma_f32 v[104:105], v[86:87], v[104:105], v[0:1]
	v_pk_fma_f32 v[102:103], v[84:85], v[102:103], v[2:3]
	v_cvt_pk_bf16_f32 v104, v104, v105
	v_cvt_pk_bf16_f32 v105, v102, v103
	global_store_dwordx2 v[100:101], v[104:105], off offset:288
	ds_read2_b32 v[100:101], v196 offset0:32 offset1:48
	v_add_u32_e32 v102, 32, v78
	v_ashrrev_i32_e32 v103, 31, v102
	v_lshlrev_b64 v[102:103], 12, v[102:103]
	v_lshl_add_u64 v[102:103], s[26:27], 0, v[102:103]
	s_waitcnt lgkmcnt(0)
	v_pk_mul_f32 v[104:105], v[172:173], v[100:101] op_sel_hi:[1,0]
	v_pk_mul_f32 v[106:107], v[174:175], v[100:101] op_sel_hi:[1,0]
	v_pk_fma_f32 v[104:105], v[98:99], v[104:105], v[12:13]
	v_pk_fma_f32 v[106:107], v[96:97], v[106:107], v[14:15]
	v_lshl_add_u64 v[102:103], v[102:103], 0, v[74:75]
	v_cvt_pk_bf16_f32 v104, v104, v105
	v_cvt_pk_bf16_f32 v105, v106, v107
	global_store_dwordx2 v[102:103], v[104:105], off
	v_pk_mul_f32 v[104:105], v[168:169], v[100:101] op_sel_hi:[1,0]
	v_pk_mul_f32 v[106:107], v[170:171], v[100:101] op_sel_hi:[1,0]
	v_pk_fma_f32 v[104:105], v[94:95], v[104:105], v[8:9]
	v_pk_fma_f32 v[106:107], v[92:93], v[106:107], v[10:11]
	v_cvt_pk_bf16_f32 v104, v104, v105
	v_cvt_pk_bf16_f32 v105, v106, v107
	global_store_dwordx2 v[102:103], v[104:105], off offset:32
	v_pk_mul_f32 v[104:105], v[164:165], v[100:101] op_sel_hi:[1,0]
	v_pk_mul_f32 v[106:107], v[166:167], v[100:101] op_sel_hi:[1,0]
	v_pk_fma_f32 v[104:105], v[90:91], v[104:105], v[4:5]
	v_pk_fma_f32 v[106:107], v[88:89], v[106:107], v[6:7]
	v_cvt_pk_bf16_f32 v104, v104, v105
	v_cvt_pk_bf16_f32 v105, v106, v107
	global_store_dwordx2 v[102:103], v[104:105], off offset:256
	v_pk_mul_f32 v[104:105], v[160:161], v[100:101] op_sel_hi:[1,0]
	v_pk_mul_f32 v[106:107], v[162:163], v[100:101] op_sel_hi:[1,0]
	v_pk_fma_f32 v[104:105], v[86:87], v[104:105], v[0:1]
	v_pk_fma_f32 v[106:107], v[84:85], v[106:107], v[2:3]
	v_cvt_pk_bf16_f32 v104, v104, v105
	v_cvt_pk_bf16_f32 v105, v106, v107
	global_store_dwordx2 v[102:103], v[104:105], off offset:288
	v_add_u32_e32 v102, 48, v78
	v_ashrrev_i32_e32 v103, 31, v102
	v_mov_b32_e32 v100, v101
	v_lshlrev_b64 v[102:103], 12, v[102:103]
	v_pk_mul_f32 v[104:105], v[156:157], v[100:101] op_sel_hi:[1,0]
	v_pk_mul_f32 v[106:107], v[158:159], v[100:101] op_sel_hi:[1,0]
	v_lshl_add_u64 v[102:103], s[26:27], 0, v[102:103]
	v_pk_fma_f32 v[106:107], v[96:97], v[106:107], v[14:15]
	v_pk_fma_f32 v[104:105], v[98:99], v[104:105], v[12:13]
	v_lshl_add_u64 v[102:103], v[102:103], 0, v[74:75]
	v_cvt_pk_bf16_f32 v104, v104, v105
	v_cvt_pk_bf16_f32 v105, v106, v107
	global_store_dwordx2 v[102:103], v[104:105], off
	v_pk_mul_f32 v[104:105], v[152:153], v[100:101] op_sel_hi:[1,0]
	v_pk_mul_f32 v[106:107], v[154:155], v[100:101] op_sel_hi:[1,0]
	v_pk_fma_f32 v[104:105], v[94:95], v[104:105], v[8:9]
	v_pk_fma_f32 v[106:107], v[92:93], v[106:107], v[10:11]
	v_cvt_pk_bf16_f32 v104, v104, v105
	v_cvt_pk_bf16_f32 v105, v106, v107
	global_store_dwordx2 v[102:103], v[104:105], off offset:32
	v_pk_mul_f32 v[104:105], v[148:149], v[100:101] op_sel_hi:[1,0]
	v_pk_mul_f32 v[106:107], v[150:151], v[100:101] op_sel_hi:[1,0]
	v_pk_fma_f32 v[104:105], v[90:91], v[104:105], v[4:5]
	v_pk_fma_f32 v[106:107], v[88:89], v[106:107], v[6:7]
	v_cvt_pk_bf16_f32 v104, v104, v105
	v_cvt_pk_bf16_f32 v105, v106, v107
	global_store_dwordx2 v[102:103], v[104:105], off offset:256
	v_pk_mul_f32 v[104:105], v[144:145], v[100:101] op_sel_hi:[1,0]
	v_pk_mul_f32 v[100:101], v[146:147], v[100:101] op_sel_hi:[1,0]
	v_pk_fma_f32 v[104:105], v[86:87], v[104:105], v[0:1]
	v_pk_fma_f32 v[100:101], v[84:85], v[100:101], v[2:3]
	v_cvt_pk_bf16_f32 v104, v104, v105
	v_cvt_pk_bf16_f32 v105, v100, v101
	ds_read2_b32 v[100:101], v196 offset0:128 offset1:144
	global_store_dwordx2 v[102:103], v[104:105], off offset:288
	v_add_u32_e32 v102, 0x80, v78
	v_ashrrev_i32_e32 v103, 31, v102
	v_lshlrev_b64 v[102:103], 12, v[102:103]
	s_waitcnt lgkmcnt(0)
	v_pk_mul_f32 v[44:45], v[44:45], v[100:101] op_sel_hi:[1,0]
	v_pk_mul_f32 v[46:47], v[46:47], v[100:101] op_sel_hi:[1,0]
	v_lshl_add_u64 v[102:103], s[26:27], 0, v[102:103]
	v_pk_fma_f32 v[46:47], v[84:85], v[46:47], v[2:3]
	v_pk_fma_f32 v[44:45], v[86:87], v[44:45], v[0:1]
	v_lshl_add_u64 v[102:103], v[102:103], 0, v[74:75]
	v_cvt_pk_bf16_f32 v44, v44, v45
	v_cvt_pk_bf16_f32 v45, v46, v47
	global_store_dwordx2 v[102:103], v[44:45], off offset:288
	v_add_u32_e32 v44, 0x90, v78
	v_ashrrev_i32_e32 v45, 31, v44
	v_mov_b32_e32 v46, v101
	v_lshlrev_b64 v[44:45], 12, v[44:45]
	v_pk_mul_f32 v[24:25], v[24:25], v[46:47] op_sel_hi:[1,0]
	v_pk_mul_f32 v[26:27], v[26:27], v[46:47] op_sel_hi:[1,0]
	v_lshl_add_u64 v[44:45], s[26:27], 0, v[44:45]
	v_pk_fma_f32 v[26:27], v[84:85], v[26:27], v[2:3]
	v_pk_fma_f32 v[24:25], v[86:87], v[24:25], v[0:1]
	v_lshl_add_u64 v[44:45], v[44:45], 0, v[74:75]
	v_cvt_pk_bf16_f32 v24, v24, v25
	v_cvt_pk_bf16_f32 v25, v26, v27
	global_store_dwordx2 v[44:45], v[24:25], off offset:288
	ds_read2_b32 v[24:25], v196 offset0:160 offset1:176
	v_add_u32_e32 v26, 0xa0, v78
	v_ashrrev_i32_e32 v27, 31, v26
	v_lshlrev_b64 v[26:27], 12, v[26:27]
	v_lshl_add_u64 v[26:27], s[26:27], 0, v[26:27]
	s_waitcnt lgkmcnt(0)
	v_pk_mul_f32 v[16:17], v[16:17], v[24:25] op_sel_hi:[1,0]
	v_pk_mul_f32 v[18:19], v[18:19], v[24:25] op_sel_hi:[1,0]
	v_pk_fma_f32 v[16:17], v[90:91], v[16:17], v[4:5]
	v_pk_fma_f32 v[18:19], v[88:89], v[18:19], v[6:7]
	v_lshl_add_u64 v[26:27], v[26:27], 0, v[74:75]
	v_cvt_pk_bf16_f32 v16, v16, v17
	v_cvt_pk_bf16_f32 v17, v18, v19
	global_store_dwordx2 v[26:27], v[16:17], off offset:256
	v_pk_mul_f32 v[16:17], v[80:81], v[24:25] op_sel_hi:[1,0]
	v_pk_mul_f32 v[18:19], v[82:83], v[24:25] op_sel_hi:[1,0]
	v_pk_fma_f32 v[16:17], v[86:87], v[16:17], v[0:1]
	v_pk_fma_f32 v[18:19], v[84:85], v[18:19], v[2:3]
	v_pk_mul_f32 v[32:33], v[32:33], v[46:47] op_sel_hi:[1,0]
	v_pk_mul_f32 v[34:35], v[34:35], v[46:47] op_sel_hi:[1,0]
	v_cvt_pk_bf16_f32 v16, v16, v17
	v_cvt_pk_bf16_f32 v17, v18, v19
	v_pk_fma_f32 v[34:35], v[88:89], v[34:35], v[6:7]
	v_pk_fma_f32 v[32:33], v[90:91], v[32:33], v[4:5]
	global_store_dwordx2 v[26:27], v[16:17], off offset:288
	v_add_u32_e32 v16, 0xb0, v78
	v_cvt_pk_bf16_f32 v32, v32, v33
	v_cvt_pk_bf16_f32 v33, v34, v35
	v_ashrrev_i32_e32 v17, 31, v16
	v_mov_b32_e32 v18, v25
	v_pk_mul_f32 v[60:61], v[60:61], v[100:101] op_sel_hi:[1,0]
	v_pk_mul_f32 v[62:63], v[62:63], v[100:101] op_sel_hi:[1,0]
	v_pk_mul_f32 v[48:49], v[48:49], v[46:47] op_sel_hi:[1,0]
	v_pk_mul_f32 v[50:51], v[50:51], v[46:47] op_sel_hi:[1,0]
	global_store_dwordx2 v[44:45], v[32:33], off offset:256
	v_pk_mul_f32 v[32:33], v[36:37], v[24:25] op_sel_hi:[1,0]
	v_pk_mul_f32 v[34:35], v[38:39], v[24:25] op_sel_hi:[1,0]
	v_pk_mul_f32 v[28:29], v[28:29], v[24:25] op_sel_hi:[1,0]
	v_pk_mul_f32 v[30:31], v[30:31], v[24:25] op_sel_hi:[1,0]
	v_lshlrev_b64 v[16:17], 12, v[16:17]
	v_pk_mul_f32 v[24:25], v[76:77], v[18:19] op_sel_hi:[1,0]
	v_pk_mul_f32 v[22:23], v[22:23], v[18:19] op_sel_hi:[1,0]
	v_pk_fma_f32 v[62:63], v[96:97], v[62:63], v[14:15]
	v_pk_fma_f32 v[60:61], v[98:99], v[60:61], v[12:13]
	v_pk_fma_f32 v[50:51], v[96:97], v[50:51], v[14:15]
	v_pk_fma_f32 v[48:49], v[98:99], v[48:49], v[12:13]
	v_pk_fma_f32 v[34:35], v[96:97], v[34:35], v[14:15]
	v_pk_fma_f32 v[32:33], v[98:99], v[32:33], v[12:13]
	v_lshl_add_u64 v[16:17], s[26:27], 0, v[16:17]
	v_pk_fma_f32 v[14:15], v[96:97], v[22:23], v[14:15]
	v_pk_fma_f32 v[12:13], v[98:99], v[24:25], v[12:13]
	v_lshl_add_u64 v[16:17], v[16:17], 0, v[74:75]
	v_cvt_pk_bf16_f32 v12, v12, v13
	v_cvt_pk_bf16_f32 v13, v14, v15
	v_pk_mul_f32 v[56:57], v[56:57], v[100:101] op_sel_hi:[1,0]
	v_pk_mul_f32 v[58:59], v[58:59], v[100:101] op_sel_hi:[1,0]
	v_pk_mul_f32 v[40:41], v[40:41], v[46:47] op_sel_hi:[1,0]
	v_pk_mul_f32 v[42:43], v[42:43], v[46:47] op_sel_hi:[1,0]
	global_store_dwordx2 v[16:17], v[12:13], off
	v_pk_mul_f32 v[12:13], v[72:73], v[18:19] op_sel_hi:[1,0]
	v_pk_mul_f32 v[14:15], v[20:21], v[18:19] op_sel_hi:[1,0]
	v_pk_fma_f32 v[58:59], v[92:93], v[58:59], v[10:11]
	v_pk_fma_f32 v[56:57], v[94:95], v[56:57], v[8:9]
	v_pk_fma_f32 v[42:43], v[92:93], v[42:43], v[10:11]
	v_pk_fma_f32 v[40:41], v[94:95], v[40:41], v[8:9]
	v_pk_fma_f32 v[30:31], v[92:93], v[30:31], v[10:11]
	v_pk_fma_f32 v[28:29], v[94:95], v[28:29], v[8:9]
	v_pk_fma_f32 v[10:11], v[92:93], v[14:15], v[10:11]
	v_pk_fma_f32 v[8:9], v[94:95], v[12:13], v[8:9]
	v_pk_mul_f32 v[52:53], v[52:53], v[100:101] op_sel_hi:[1,0]
	v_cvt_pk_bf16_f32 v8, v8, v9
	v_cvt_pk_bf16_f32 v9, v10, v11
	v_pk_mul_f32 v[54:55], v[54:55], v[100:101] op_sel_hi:[1,0]
	global_store_dwordx2 v[16:17], v[8:9], off offset:32
	v_pk_mul_f32 v[8:9], v[68:69], v[18:19] op_sel_hi:[1,0]
	v_pk_mul_f32 v[10:11], v[70:71], v[18:19] op_sel_hi:[1,0]
	v_pk_fma_f32 v[54:55], v[88:89], v[54:55], v[6:7]
	v_pk_fma_f32 v[52:53], v[90:91], v[52:53], v[4:5]
	v_pk_fma_f32 v[6:7], v[88:89], v[10:11], v[6:7]
	v_pk_fma_f32 v[4:5], v[90:91], v[8:9], v[4:5]
	v_cvt_pk_bf16_f32 v60, v60, v61
	v_cvt_pk_bf16_f32 v4, v4, v5
	v_cvt_pk_bf16_f32 v5, v6, v7
	global_store_dwordx2 v[16:17], v[4:5], off offset:256
	v_pk_mul_f32 v[4:5], v[64:65], v[18:19] op_sel_hi:[1,0]
	v_pk_mul_f32 v[6:7], v[66:67], v[18:19] op_sel_hi:[1,0]
	v_pk_fma_f32 v[0:1], v[86:87], v[4:5], v[0:1]
	v_pk_fma_f32 v[2:3], v[84:85], v[6:7], v[2:3]
	v_cvt_pk_bf16_f32 v61, v62, v63
	v_cvt_pk_bf16_f32 v56, v56, v57
	v_cvt_pk_bf16_f32 v57, v58, v59
	v_cvt_pk_bf16_f32 v52, v52, v53
	v_cvt_pk_bf16_f32 v53, v54, v55
	v_cvt_pk_bf16_f32 v48, v48, v49
	v_cvt_pk_bf16_f32 v49, v50, v51
	v_cvt_pk_bf16_f32 v40, v40, v41
	v_cvt_pk_bf16_f32 v41, v42, v43
	v_cvt_pk_bf16_f32 v32, v32, v33
	v_cvt_pk_bf16_f32 v33, v34, v35
	v_cvt_pk_bf16_f32 v28, v28, v29
	v_cvt_pk_bf16_f32 v29, v30, v31
	v_cvt_pk_bf16_f32 v0, v0, v1
	v_cvt_pk_bf16_f32 v1, v2, v3
	global_store_dwordx2 v[102:103], v[60:61], off
	global_store_dwordx2 v[102:103], v[56:57], off offset:32
	global_store_dwordx2 v[102:103], v[52:53], off offset:256
	global_store_dwordx2 v[44:45], v[48:49], off
	global_store_dwordx2 v[44:45], v[40:41], off offset:32
	global_store_dwordx2 v[26:27], v[32:33], off
	global_store_dwordx2 v[26:27], v[28:29], off offset:32
	global_store_dwordx2 v[16:17], v[0:1], off offset:288
.LBB0_865:
	s_waitcnt vmcnt(0)
	s_barrier
	s_mov_b64 s[4:5], exec
	v_readlane_b32 s0, v255, 1
	v_readlane_b32 s1, v255, 2
	s_and_b64 s[0:1], s[4:5], s[0:1]
	s_mov_b64 exec, s[0:1]
	s_cbranch_execz .Lgb5_others
	s_getreg_b32 s0, hwreg(HW_REG_XCC_ID, 0, 4)
	v_mov_b32_e32 v0, 0x23fc0
	ds_read_b64 v[2:3], v0
	s_and_b32 s0, s0, 15
	s_lshl_b32 s1, s0, 8
	s_add_u32 s6, s54, s1
	s_addc_u32 s7, s55, 0
	v_mov_b32_e32 v0, 0x1000
	v_mov_b32_e32 v1, 1
	global_atomic_add v1, v0, v1, s[6:7] offset:1024 sc0
	s_waitcnt lgkmcnt(0)
	v_readfirstlane_b32 s8, v2
	v_readfirstlane_b32 s9, v3
	s_mul_i32 s8, s8, 4
	s_mul_i32 s9, s9, 4
	v_mov_b32_e32 v0, 0x3000
	s_waitcnt vmcnt(0)
	v_readfirstlane_b32 s0, v1
	s_add_u32 s0, s0, 1
	s_cmp_lg_u32 s0, s8
	s_cbranch_scc0 .Lgb5_lead
	s_branch .Lgb5_wait

.LBB0_985:
	s_waitcnt vmcnt(0)
	s_waitcnt vmcnt(0)
	s_barrier
	s_mov_b64 s[4:5], exec
	v_readlane_b32 s0, v255, 1
	v_readlane_b32 s1, v255, 2
	s_and_b64 s[0:1], s[4:5], s[0:1]
	s_mov_b64 exec, s[0:1]
	s_cbranch_execz .Lgb6_others
	s_getreg_b32 s0, hwreg(HW_REG_XCC_ID, 0, 4)
	v_mov_b32_e32 v0, 0x23fc0
	ds_read_b64 v[2:3], v0
	s_and_b32 s0, s0, 15
	s_lshl_b32 s1, s0, 8
	s_add_u32 s6, s54, s1
	s_addc_u32 s7, s55, 0
	v_mov_b32_e32 v0, 0x1000
	v_mov_b32_e32 v1, 1
	global_atomic_add v1, v0, v1, s[6:7] offset:1024 sc0
	s_waitcnt lgkmcnt(0)
	v_readfirstlane_b32 s8, v2
	v_readfirstlane_b32 s9, v3
	s_mul_i32 s8, s8, 5
	s_mul_i32 s9, s9, 5
	v_mov_b32_e32 v0, 0x3000
	s_waitcnt vmcnt(0)
	v_readfirstlane_b32 s0, v1
	s_add_u32 s0, s0, 1
	s_cmp_lg_u32 s0, s8
	s_cbranch_scc0 .Lgb6_lead
	s_branch .Lgb6_wait
